# attention K/V chunk LDS-DMA issue loops rewritten as straight-line code (reciprocal-multiply row/segment split, saddr loads)
# speedup vs baseline: 1.0070x; 1.0070x over previous
; __device__ __forceinline__ bool attn_unit(const Ptrs& P, LAS unsigned char* lds, int unit, int tid, int wave, int lane, bool pre, int nxt) {
;     ...
;     if (!pre) { if (n == 0) AT_DMA(1); else AT_DMA(0); }
.LBB9_314:
	s_lshl_b32 s48, s50, 10
	v_mov_b32_e32 v4, v192
	v_mul_u32_u24_e32 v5, 0x1c72, v4
	v_lshrrev_b32_e32 v5, 16, v5
	v_mul_u32_u24_e32 v6, 9, v5
	v_sub_u32_e32 v6, v4, v6
	v_cmp_ne_u32_e32 vcc, 8, v6
	v_lshlrev_b32_e32 v6, 4, v6
	s_add_i32 m0, s48, 0x0
	v_cndmask_b32_e32 v6, 0, v6, vcc
	v_lshl_add_u32 v4, v5, 9, v6
	global_load_lds_dwordx4 v4, s[68:69]
	v_add_u32_e32 v4, 512, v192
	v_mul_u32_u24_e32 v5, 0x1c72, v4
	v_lshrrev_b32_e32 v5, 16, v5
	v_mul_u32_u24_e32 v6, 9, v5
	v_sub_u32_e32 v6, v4, v6
	v_cmp_ne_u32_e32 vcc, 8, v6
	v_lshlrev_b32_e32 v6, 4, v6
	s_add_i32 m0, s48, 0x2000
	v_cndmask_b32_e32 v6, 0, v6, vcc
	v_lshl_add_u32 v4, v5, 9, v6
	global_load_lds_dwordx4 v4, s[68:69]
	s_cmp_lt_u32 s50, 2
	s_cbranch_scc1 .Ldk_s0
	v_add_u32_e32 v4, 1024, v193
	v_mul_u32_u24_e32 v5, 0xf10, v4
	v_lshrrev_b32_e32 v5, 16, v5
	v_mul_u32_u24_e32 v6, 17, v5
	v_sub_u32_e32 v6, v4, v6
	v_cmp_ne_u32_e32 vcc, 16, v6
	v_lshlrev_b32_e32 v6, 4, v6
	s_add_i32 m0, s48, 0x4000
	v_cndmask_b32_e32 v6, 0, v6, vcc
	v_lshl_add_u32 v4, v5, 13, v6
	global_load_lds_dwordx4 v4, s[84:85]
	s_branch .Ldj_s0
.Ldk_s0:
	v_add_u32_e32 v4, 1024, v192
	v_mul_u32_u24_e32 v5, 0x1c72, v4
	v_lshrrev_b32_e32 v5, 16, v5
	v_mul_u32_u24_e32 v6, 9, v5
	v_sub_u32_e32 v6, v4, v6
	v_cmp_ne_u32_e32 vcc, 8, v6
	v_lshlrev_b32_e32 v6, 4, v6
	s_add_i32 m0, s48, 0x4000
	v_cndmask_b32_e32 v6, 0, v6, vcc
	v_lshl_add_u32 v4, v5, 9, v6
	global_load_lds_dwordx4 v4, s[68:69]
.Ldj_s0:
	v_add_u32_e32 v4, 1536, v193
	v_mul_u32_u24_e32 v5, 0xf10, v4
	v_lshrrev_b32_e32 v5, 16, v5
	v_mul_u32_u24_e32 v6, 17, v5
	v_sub_u32_e32 v6, v4, v6
	v_cmp_ne_u32_e32 vcc, 16, v6
	v_lshlrev_b32_e32 v6, 4, v6
	s_add_i32 m0, s48, 0x6000
	v_cndmask_b32_e32 v6, 0, v6, vcc
	v_lshl_add_u32 v4, v5, 13, v6
	global_load_lds_dwordx4 v4, s[84:85]
	s_cmp_gt_u32 s50, 2
	s_cbranch_scc1 .Lde_s0
	v_add_u32_e32 v4, 2048, v193
	v_mul_u32_u24_e32 v5, 0xf10, v4
	v_lshrrev_b32_e32 v5, 16, v5
	v_mul_u32_u24_e32 v6, 17, v5
	v_sub_u32_e32 v6, v4, v6
	v_cmp_ne_u32_e32 vcc, 16, v6
	v_lshlrev_b32_e32 v6, 4, v6
	s_add_i32 m0, s48, 0x8000
	v_cndmask_b32_e32 v6, 0, v6, vcc
	v_lshl_add_u32 v4, v5, 13, v6
	global_load_lds_dwordx4 v4, s[84:85]
.Lde_s0:
.LBB9_318:
	v_readlane_b32 s76, v250, 8
	s_cbranch_execz .LBB9_320
	s_branch .LBB9_329

; #define AT_SYNC() do { asm volatile("s_waitcnt vmcnt(0) lgkmcnt(0)" ::: "memory"); __builtin_amdgcn_s_barrier(); asm volatile("" ::: "memory"); } while (0)
; __device__ __forceinline__ bool attn_unit(const Ptrs& P, LAS unsigned char* lds, int unit, int tid, int wave, int lane, bool pre, int nxt) {
;     ...
;     if (!pre) { if (n == 0) AT_DMA(1); else AT_DMA(0); }
;     AT_SYNC();
;     const int n2 = nxt & 31; const bool pf = nxt >= 0 && n2 != 0;
; #pragma unroll
;     for (int c = 0; c < 5; ++c) {
;         if (c == 0 && n == 0) continue;
;         if (c == 2 && n == 31) continue;
;         if (c == 0) AT_DMA(1);
.LBB9_324:
	s_lshl_b32 s48, s50, 10
	v_mov_b32_e32 v4, v192
	v_mul_u32_u24_e32 v5, 0x1c72, v4
	v_lshrrev_b32_e32 v5, 16, v5
	v_mul_u32_u24_e32 v6, 9, v5
	v_sub_u32_e32 v6, v4, v6
	v_cmp_ne_u32_e32 vcc, 8, v6
	v_lshlrev_b32_e32 v6, 4, v6
	s_add_i32 m0, s48, 0x8c00
	v_cndmask_b32_e32 v6, 0, v6, vcc
	v_lshl_add_u32 v4, v5, 9, v6
	global_load_lds_dwordx4 v4, s[96:97]
	v_add_u32_e32 v4, 512, v192
	v_mul_u32_u24_e32 v5, 0x1c72, v4
	v_lshrrev_b32_e32 v5, 16, v5
	v_mul_u32_u24_e32 v6, 9, v5
	v_sub_u32_e32 v6, v4, v6
	v_cmp_ne_u32_e32 vcc, 8, v6
	v_lshlrev_b32_e32 v6, 4, v6
	s_add_i32 m0, s48, 0xac00
	v_cndmask_b32_e32 v6, 0, v6, vcc
	v_lshl_add_u32 v4, v5, 9, v6
	global_load_lds_dwordx4 v4, s[96:97]
	s_cmp_lt_u32 s50, 2
	s_cbranch_scc1 .Ldk_s1
	v_add_u32_e32 v4, 1024, v193
	v_mul_u32_u24_e32 v5, 0xf10, v4
	v_lshrrev_b32_e32 v5, 16, v5
	v_mul_u32_u24_e32 v6, 17, v5
	v_sub_u32_e32 v6, v4, v6
	v_cmp_ne_u32_e32 vcc, 16, v6
	v_lshlrev_b32_e32 v6, 4, v6
	s_add_i32 m0, s48, 0xcc00
	v_cndmask_b32_e32 v6, 0, v6, vcc
	v_lshl_add_u32 v4, v5, 13, v6
	global_load_lds_dwordx4 v4, s[68:69]
	s_branch .Ldj_s1
.Ldk_s1:
	v_add_u32_e32 v4, 1024, v192
	v_mul_u32_u24_e32 v5, 0x1c72, v4
	v_lshrrev_b32_e32 v5, 16, v5
	v_mul_u32_u24_e32 v6, 9, v5
	v_sub_u32_e32 v6, v4, v6
	v_cmp_ne_u32_e32 vcc, 8, v6
	v_lshlrev_b32_e32 v6, 4, v6
	s_add_i32 m0, s48, 0xcc00
	v_cndmask_b32_e32 v6, 0, v6, vcc
	v_lshl_add_u32 v4, v5, 9, v6
	global_load_lds_dwordx4 v4, s[96:97]
.Ldj_s1:
	v_add_u32_e32 v4, 1536, v193
	v_mul_u32_u24_e32 v5, 0xf10, v4
	v_lshrrev_b32_e32 v5, 16, v5
	v_mul_u32_u24_e32 v6, 17, v5
	v_sub_u32_e32 v6, v4, v6
	v_cmp_ne_u32_e32 vcc, 16, v6
	v_lshlrev_b32_e32 v6, 4, v6
	s_add_i32 m0, s48, 0xec00
	v_cndmask_b32_e32 v6, 0, v6, vcc
	v_lshl_add_u32 v4, v5, 13, v6
	global_load_lds_dwordx4 v4, s[68:69]
	s_cmp_gt_u32 s50, 2
	s_cbranch_scc1 .Lde_s1
	v_add_u32_e32 v4, 2048, v193
	v_mul_u32_u24_e32 v5, 0xf10, v4
	v_lshrrev_b32_e32 v5, 16, v5
	v_mul_u32_u24_e32 v6, 17, v5
	v_sub_u32_e32 v6, v4, v6
	v_cmp_ne_u32_e32 vcc, 16, v6
	v_lshlrev_b32_e32 v6, 4, v6
	s_add_i32 m0, s48, 0x10c00
	v_cndmask_b32_e32 v6, 0, v6, vcc
	v_lshl_add_u32 v4, v5, 13, v6
	global_load_lds_dwordx4 v4, s[68:69]
.Lde_s1:
.LBB9_328:
	v_readlane_b32 s76, v250, 8

; #define AT_SYNC() do { asm volatile("s_waitcnt vmcnt(0) lgkmcnt(0)" ::: "memory"); __builtin_amdgcn_s_barrier(); asm volatile("" ::: "memory"); } while (0)
; __device__ __forceinline__ bool attn_unit(const Ptrs& P, LAS unsigned char* lds, int unit, int tid, int wave, int lane, bool pre, int nxt) {
;     ...
;     if (!pre) { if (n == 0) AT_DMA(1); else AT_DMA(0); }
;     AT_SYNC();
;     const int n2 = nxt & 31; const bool pf = nxt >= 0 && n2 != 0;
; #pragma unroll
;     for (int c = 0; c < 5; ++c) {
;         if (c == 0 && n == 0) continue;
;         if (c == 2 && n == 31) continue;
;         if (c == 0) AT_DMA(1);
.LBB9_334:
	s_lshl_b32 s48, s50, 10
	v_mov_b32_e32 v4, v192
	v_mul_u32_u24_e32 v5, 0x1c72, v4
	v_lshrrev_b32_e32 v5, 16, v5
	v_mul_u32_u24_e32 v6, 9, v5
	v_sub_u32_e32 v6, v4, v6
	v_cmp_ne_u32_e32 vcc, 8, v6
	v_lshlrev_b32_e32 v6, 4, v6
	s_add_i32 m0, s48, 0x8c00
	v_cndmask_b32_e32 v6, 0, v6, vcc
	v_lshl_add_u32 v4, v5, 9, v6
	global_load_lds_dwordx4 v4, s[84:85]
	v_add_u32_e32 v4, 512, v192
	v_mul_u32_u24_e32 v5, 0x1c72, v4
	v_lshrrev_b32_e32 v5, 16, v5
	v_mul_u32_u24_e32 v6, 9, v5
	v_sub_u32_e32 v6, v4, v6
	v_cmp_ne_u32_e32 vcc, 8, v6
	v_lshlrev_b32_e32 v6, 4, v6
	s_add_i32 m0, s48, 0xac00
	v_cndmask_b32_e32 v6, 0, v6, vcc
	v_lshl_add_u32 v4, v5, 9, v6
	global_load_lds_dwordx4 v4, s[84:85]
	s_cmp_lt_u32 s50, 2
	s_cbranch_scc1 .Ldk_s2
	v_add_u32_e32 v4, 1024, v193
	v_mul_u32_u24_e32 v5, 0xf10, v4
	v_lshrrev_b32_e32 v5, 16, v5
	v_mul_u32_u24_e32 v6, 17, v5
	v_sub_u32_e32 v6, v4, v6
	v_cmp_ne_u32_e32 vcc, 16, v6
	v_lshlrev_b32_e32 v6, 4, v6
	s_add_i32 m0, s48, 0xcc00
	v_cndmask_b32_e32 v6, 0, v6, vcc
	v_lshl_add_u32 v4, v5, 13, v6
	global_load_lds_dwordx4 v4, s[74:75]
	s_branch .Ldj_s2
.Ldk_s2:
	v_add_u32_e32 v4, 1024, v192
	v_mul_u32_u24_e32 v5, 0x1c72, v4
	v_lshrrev_b32_e32 v5, 16, v5
	v_mul_u32_u24_e32 v6, 9, v5
	v_sub_u32_e32 v6, v4, v6
	v_cmp_ne_u32_e32 vcc, 8, v6
	v_lshlrev_b32_e32 v6, 4, v6
	s_add_i32 m0, s48, 0xcc00
	v_cndmask_b32_e32 v6, 0, v6, vcc
	v_lshl_add_u32 v4, v5, 9, v6
	global_load_lds_dwordx4 v4, s[84:85]
.Ldj_s2:
	v_add_u32_e32 v4, 1536, v193
	v_mul_u32_u24_e32 v5, 0xf10, v4
	v_lshrrev_b32_e32 v5, 16, v5
	v_mul_u32_u24_e32 v6, 17, v5
	v_sub_u32_e32 v6, v4, v6
	v_cmp_ne_u32_e32 vcc, 16, v6
	v_lshlrev_b32_e32 v6, 4, v6
	s_add_i32 m0, s48, 0xec00
	v_cndmask_b32_e32 v6, 0, v6, vcc
	v_lshl_add_u32 v4, v5, 13, v6
	global_load_lds_dwordx4 v4, s[74:75]
	s_cmp_gt_u32 s50, 2
	s_cbranch_scc1 .Lde_s2
	v_add_u32_e32 v4, 2048, v193
	v_mul_u32_u24_e32 v5, 0xf10, v4
	v_lshrrev_b32_e32 v5, 16, v5
	v_mul_u32_u24_e32 v6, 17, v5
	v_sub_u32_e32 v6, v4, v6
	v_cmp_ne_u32_e32 vcc, 16, v6
	v_lshlrev_b32_e32 v6, 4, v6
	s_add_i32 m0, s48, 0x10c00
	v_cndmask_b32_e32 v6, 0, v6, vcc
	v_lshl_add_u32 v4, v5, 13, v6
	global_load_lds_dwordx4 v4, s[74:75]
.Lde_s2:
.LBB9_338:
	v_mov_b32_e32 v16, v1
	v_mov_b32_e32 v17, v1
	v_mov_b32_e32 v0, v1
	v_mov_b32_e32 v2, v1
	v_mov_b32_e32 v3, v1
	v_mov_b32_e32 v4, v1
	v_mov_b32_e32 v5, v1
	v_mov_b32_e32 v6, v1
	v_mov_b32_e32 v7, v1
	v_mov_b32_e32 v8, v1
	v_mov_b32_e32 v9, v1
	v_mov_b32_e32 v10, v1
	v_mov_b32_e32 v11, v1
	v_mov_b32_e32 v12, v1
	v_mov_b32_e32 v13, v1
	v_mov_b32_e32 v14, v1
	v_mov_b32_e32 v15, v1
	v_mov_b64_e32 v[64:65], v[16:17]
	v_mov_b64_e32 v[48:49], v[16:17]
	v_mov_b64_e32 v[80:81], v[16:17]
	s_mov_b32 s47, 0
	v_mov_b32_e32 v204, v196
	v_mov_b32_e32 v205, v195
	v_mov_b32_e32 v206, v194
	v_mov_b64_e32 v[62:63], v[14:15]
	v_mov_b64_e32 v[60:61], v[12:13]
	v_mov_b64_e32 v[58:59], v[10:11]
	v_mov_b64_e32 v[56:57], v[8:9]
	v_mov_b64_e32 v[54:55], v[6:7]
	v_mov_b64_e32 v[52:53], v[4:5]
	v_mov_b64_e32 v[50:51], v[2:3]
	v_mov_b64_e32 v[46:47], v[14:15]
	v_mov_b64_e32 v[44:45], v[12:13]
	v_mov_b64_e32 v[42:43], v[10:11]
	v_mov_b64_e32 v[40:41], v[8:9]
	v_mov_b64_e32 v[38:39], v[6:7]
	v_mov_b64_e32 v[36:37], v[4:5]
	v_mov_b64_e32 v[34:35], v[2:3]
	v_mov_b64_e32 v[78:79], v[14:15]
	v_mov_b64_e32 v[76:77], v[12:13]
	v_mov_b64_e32 v[74:75], v[10:11]
	v_mov_b64_e32 v[72:73], v[8:9]
	v_mov_b64_e32 v[70:71], v[6:7]
	v_mov_b64_e32 v[68:69], v[4:5]
	v_mov_b64_e32 v[66:67], v[2:3]
	v_mov_b64_e32 v[182:183], v[0:1]
	s_branch .LBB9_341

.LBB9_356:
	s_lshl_b32 s48, s50, 10
	v_mov_b32_e32 v84, v192
	v_mul_u32_u24_e32 v85, 0x1c72, v84
	v_lshrrev_b32_e32 v85, 16, v85
	v_mul_u32_u24_e32 v86, 9, v85
	v_sub_u32_e32 v86, v84, v86
	v_cmp_ne_u32_e32 vcc, 8, v86
	v_lshlrev_b32_e32 v86, 4, v86
	s_add_i32 m0, s48, 0x11800
	v_cndmask_b32_e32 v86, 0, v86, vcc
	v_lshl_add_u32 v84, v85, 9, v86
	global_load_lds_dwordx4 v84, s[96:97]
	v_add_u32_e32 v84, 512, v192
	v_mul_u32_u24_e32 v85, 0x1c72, v84
	v_lshrrev_b32_e32 v85, 16, v85
	v_mul_u32_u24_e32 v86, 9, v85
	v_sub_u32_e32 v86, v84, v86
	v_cmp_ne_u32_e32 vcc, 8, v86
	v_lshlrev_b32_e32 v86, 4, v86
	s_add_i32 m0, s48, 0x13800
	v_cndmask_b32_e32 v86, 0, v86, vcc
	v_lshl_add_u32 v84, v85, 9, v86
	global_load_lds_dwordx4 v84, s[96:97]
	s_cmp_lt_u32 s50, 2
	s_cbranch_scc1 .Ldk_s3
	v_add_u32_e32 v84, 1024, v193
	v_mul_u32_u24_e32 v85, 0xf10, v84
	v_lshrrev_b32_e32 v85, 16, v85
	v_mul_u32_u24_e32 v86, 17, v85
	v_sub_u32_e32 v86, v84, v86
	v_cmp_ne_u32_e32 vcc, 16, v86
	v_lshlrev_b32_e32 v86, 4, v86
	s_add_i32 m0, s48, 0x15800
	v_cndmask_b32_e32 v86, 0, v86, vcc
	v_lshl_add_u32 v84, v85, 13, v86
	global_load_lds_dwordx4 v84, s[74:75]
	s_branch .Ldj_s3
.Ldk_s3:
	v_add_u32_e32 v84, 1024, v192
	v_mul_u32_u24_e32 v85, 0x1c72, v84
	v_lshrrev_b32_e32 v85, 16, v85
	v_mul_u32_u24_e32 v86, 9, v85
	v_sub_u32_e32 v86, v84, v86
	v_cmp_ne_u32_e32 vcc, 8, v86
	v_lshlrev_b32_e32 v86, 4, v86
	s_add_i32 m0, s48, 0x15800
	v_cndmask_b32_e32 v86, 0, v86, vcc
	v_lshl_add_u32 v84, v85, 9, v86
	global_load_lds_dwordx4 v84, s[96:97]
.Ldj_s3:
	v_add_u32_e32 v84, 1536, v193
	v_mul_u32_u24_e32 v85, 0xf10, v84
	v_lshrrev_b32_e32 v85, 16, v85
	v_mul_u32_u24_e32 v86, 17, v85
	v_sub_u32_e32 v86, v84, v86
	v_cmp_ne_u32_e32 vcc, 16, v86
	v_lshlrev_b32_e32 v86, 4, v86
	s_add_i32 m0, s48, 0x17800
	v_cndmask_b32_e32 v86, 0, v86, vcc
	v_lshl_add_u32 v84, v85, 13, v86
	global_load_lds_dwordx4 v84, s[74:75]
	s_cmp_gt_u32 s50, 2
	s_cbranch_scc1 .Lde_s3
	v_add_u32_e32 v84, 2048, v193
	v_mul_u32_u24_e32 v85, 0xf10, v84
	v_lshrrev_b32_e32 v85, 16, v85
	v_mul_u32_u24_e32 v86, 17, v85
	v_sub_u32_e32 v86, v84, v86
	v_cmp_ne_u32_e32 vcc, 16, v86
	v_lshlrev_b32_e32 v86, 4, v86
	s_add_i32 m0, s48, 0x19800
	v_cndmask_b32_e32 v86, 0, v86, vcc
	v_lshl_add_u32 v84, v85, 13, v86
	global_load_lds_dwordx4 v84, s[74:75]
.Lde_s3:
.LBB9_360:
	s_mov_b64 s[74:75], 0

.LBB9_370:
	s_lshl_b32 s48, s50, 10
	v_mov_b32_e32 v84, v192
	v_mul_u32_u24_e32 v85, 0x1c72, v84
	v_lshrrev_b32_e32 v85, 16, v85
	v_mul_u32_u24_e32 v86, 9, v85
	v_sub_u32_e32 v86, v84, v86
	v_cmp_ne_u32_e32 vcc, 8, v86
	v_lshlrev_b32_e32 v86, 4, v86
	s_add_i32 m0, s48, 0x0
	v_cndmask_b32_e32 v86, 0, v86, vcc
	v_lshl_add_u32 v84, v85, 9, v86
	global_load_lds_dwordx4 v84, s[84:85]
	v_add_u32_e32 v84, 512, v192
	v_mul_u32_u24_e32 v85, 0x1c72, v84
	v_lshrrev_b32_e32 v85, 16, v85
	v_mul_u32_u24_e32 v86, 9, v85
	v_sub_u32_e32 v86, v84, v86
	v_cmp_ne_u32_e32 vcc, 8, v86
	v_lshlrev_b32_e32 v86, 4, v86
	s_add_i32 m0, s48, 0x2000
	v_cndmask_b32_e32 v86, 0, v86, vcc
	v_lshl_add_u32 v84, v85, 9, v86
	global_load_lds_dwordx4 v84, s[84:85]
	s_cmp_lt_u32 s50, 2
	s_cbranch_scc1 .Ldk_s4
	v_add_u32_e32 v84, 1024, v193
	v_mul_u32_u24_e32 v85, 0xf10, v84
	v_lshrrev_b32_e32 v85, 16, v85
	v_mul_u32_u24_e32 v86, 17, v85
	v_sub_u32_e32 v86, v84, v86
	v_cmp_ne_u32_e32 vcc, 16, v86
	v_lshlrev_b32_e32 v86, 4, v86
	s_add_i32 m0, s48, 0x4000
	v_cndmask_b32_e32 v86, 0, v86, vcc
	v_lshl_add_u32 v84, v85, 9, v86
	global_load_lds_dwordx4 v84, s[82:83]
	s_branch .Ldj_s4
.Ldk_s4:
	v_add_u32_e32 v84, 1024, v192
	v_mul_u32_u24_e32 v85, 0x1c72, v84
	v_lshrrev_b32_e32 v85, 16, v85
	v_mul_u32_u24_e32 v86, 9, v85
	v_sub_u32_e32 v86, v84, v86
	v_cmp_ne_u32_e32 vcc, 8, v86
	v_lshlrev_b32_e32 v86, 4, v86
	s_add_i32 m0, s48, 0x4000
	v_cndmask_b32_e32 v86, 0, v86, vcc
	v_lshl_add_u32 v84, v85, 9, v86
	global_load_lds_dwordx4 v84, s[84:85]
.Ldj_s4:
	v_add_u32_e32 v84, 1536, v193
	v_mul_u32_u24_e32 v85, 0xf10, v84
	v_lshrrev_b32_e32 v85, 16, v85
	v_mul_u32_u24_e32 v86, 17, v85
	v_sub_u32_e32 v86, v84, v86
	v_cmp_ne_u32_e32 vcc, 16, v86
	v_lshlrev_b32_e32 v86, 4, v86
	s_add_i32 m0, s48, 0x6000
	v_cndmask_b32_e32 v86, 0, v86, vcc
	v_lshl_add_u32 v84, v85, 9, v86
	global_load_lds_dwordx4 v84, s[82:83]
	s_cmp_gt_u32 s50, 2
	s_cbranch_scc1 .Lde_s4
	v_add_u32_e32 v84, 2048, v193
	v_mul_u32_u24_e32 v85, 0xf10, v84
	v_lshrrev_b32_e32 v85, 16, v85
	v_mul_u32_u24_e32 v86, 17, v85
	v_sub_u32_e32 v86, v84, v86
	v_cmp_ne_u32_e32 vcc, 16, v86
	v_lshlrev_b32_e32 v86, 4, v86
	s_add_i32 m0, s48, 0x8000
	v_cndmask_b32_e32 v86, 0, v86, vcc
	v_lshl_add_u32 v84, v85, 9, v86
	global_load_lds_dwordx4 v84, s[82:83]

; __device__ __forceinline__ unsigned cvtpk(float lo, float hi) { f32x2_t v = {lo, hi}; bf16x2_t b = __builtin_convertvector(v, bf16x2_t); return __builtin_bit_cast(unsigned, b); }
; #define MFMA32(a, b, c) __builtin_amdgcn_mfma_f32_32x32x16_bf16((a), (b), (c), 0, 0, 0)
; __device__ __forceinline__ bool attn_unit(const Ptrs& P, LAS unsigned char* lds, int unit, int tid, int wave, int lane, bool pre, int nxt) {
;     ...
;                 float s4 = 0.f;
; #pragma unroll
;                 for (int i = 0; i < 16; ++i) s4 += p[i];
;                 rs[cb] += s4;
; #pragma unroll
;                 for (int s = 0; s < 2; ++s) {
;                     u32x4 w; w.x = cvtpk(p[8 * s], p[8 * s + 1]); w.y = cvtpk(p[8 * s + 2], p[8 * s + 3]); w.z = cvtpk(p[8 * s + 4], p[8 * s + 5]); w.w = cvtpk(p[8 * s + 6], p[8 * s + 7]);
;                     const bf16x8_t pb = __builtin_bit_cast(bf16x8_t, w);
;                     o[0][cb] = MFMA32(vf[0][s], pb, o[0][cb]); o[1][cb] = MFMA32(vf[1][s], pb, o[1][cb]);
;                 }
.Lde_s5:
	s_branch .LBB9_367
.LBB9_380:
	v_add_f32_e32 v96, 0, v0
	v_add_f32_e32 v96, v91, v96
	v_add_f32_e32 v96, v90, v96
	v_add_f32_e32 v96, v93, v96
	v_cvt_pk_bf16_f32 v98, v0, v91
	v_cvt_pk_bf16_f32 v99, v90, v93
	v_cvt_pk_bf16_f32 v100, v92, v95
	v_cvt_pk_bf16_f32 v101, v94, v97
	v_add_f32_e32 v96, v92, v96
	v_add_f32_e32 v96, v95, v96
	v_mfma_f32_32x32x16_bf16 v[34:49], v[150:153], v[98:101], v[34:49]
	v_add_f32_e32 v96, v94, v96
	v_add_f32_e32 v96, v97, v96
	v_add_f32_e32 v96, v82, v96
	v_add_f32_e32 v96, v83, v96
	v_add_f32_e32 v96, v84, v96
	v_add_f32_e32 v96, v85, v96
	v_cvt_pk_bf16_f32 v82, v82, v83
	v_mfma_f32_32x32x16_bf16 v[2:17], v[146:149], v[98:101], v[2:17]
	v_cvt_pk_bf16_f32 v83, v84, v85
	v_cvt_pk_bf16_f32 v84, v86, v87
	v_cvt_pk_bf16_f32 v85, v88, v89
	v_add_f32_e32 v96, v86, v96
	v_add_f32_e32 v96, v87, v96
	v_add_f32_e32 v96, v88, v96
	v_add_f32_e32 v96, v89, v96
	v_mfma_f32_32x32x16_bf16 v[34:49], v[110:113], v[82:85], v[34:49]
	v_add_f32_e32 v182, v182, v96
	v_mfma_f32_32x32x16_bf16 v[2:17], v[106:109], v[82:85], v[2:17]

.LBB9_395:
	s_lshl_b32 s48, s50, 10
	v_mov_b32_e32 v84, v192
	v_mul_u32_u24_e32 v85, 0x1c72, v84
	v_lshrrev_b32_e32 v85, 16, v85
	v_mul_u32_u24_e32 v86, 9, v85
	v_sub_u32_e32 v86, v84, v86
	v_cmp_ne_u32_e32 vcc, 8, v86
	v_lshlrev_b32_e32 v86, 4, v86
	s_add_i32 m0, s48, 0x8c00
	v_cndmask_b32_e32 v86, 0, v86, vcc
	v_lshl_add_u32 v84, v85, 9, v86
	global_load_lds_dwordx4 v84, s[68:69]
	v_add_u32_e32 v84, 512, v192
	v_mul_u32_u24_e32 v85, 0x1c72, v84
	v_lshrrev_b32_e32 v85, 16, v85
	v_mul_u32_u24_e32 v86, 9, v85
	v_sub_u32_e32 v86, v84, v86
	v_cmp_ne_u32_e32 vcc, 8, v86
	v_lshlrev_b32_e32 v86, 4, v86
	s_add_i32 m0, s48, 0xac00
	v_cndmask_b32_e32 v86, 0, v86, vcc
	v_lshl_add_u32 v84, v85, 9, v86
	global_load_lds_dwordx4 v84, s[68:69]
	s_cmp_lt_u32 s50, 2
	s_cbranch_scc1 .Ldk_s6
	v_add_u32_e32 v84, 1024, v193
	v_mul_u32_u24_e32 v85, 0xf10, v84
	v_lshrrev_b32_e32 v85, 16, v85
	v_mul_u32_u24_e32 v86, 17, v85
	v_sub_u32_e32 v86, v84, v86
	v_cmp_ne_u32_e32 vcc, 16, v86
	v_lshlrev_b32_e32 v86, 4, v86
	s_add_i32 m0, s48, 0xcc00
	v_cndmask_b32_e32 v86, 0, v86, vcc
	v_lshl_add_u32 v84, v85, 9, v86
	global_load_lds_dwordx4 v84, s[70:71]
	s_branch .Ldj_s6
.Ldk_s6:
	v_add_u32_e32 v84, 1024, v192
	v_mul_u32_u24_e32 v85, 0x1c72, v84
	v_lshrrev_b32_e32 v85, 16, v85
	v_mul_u32_u24_e32 v86, 9, v85
	v_sub_u32_e32 v86, v84, v86
	v_cmp_ne_u32_e32 vcc, 8, v86
	v_lshlrev_b32_e32 v86, 4, v86
	s_add_i32 m0, s48, 0xcc00
	v_cndmask_b32_e32 v86, 0, v86, vcc
	v_lshl_add_u32 v84, v85, 9, v86
	global_load_lds_dwordx4 v84, s[68:69]
.Ldj_s6:
	v_add_u32_e32 v84, 1536, v193
	v_mul_u32_u24_e32 v85, 0xf10, v84
	v_lshrrev_b32_e32 v85, 16, v85
	v_mul_u32_u24_e32 v86, 17, v85
	v_sub_u32_e32 v86, v84, v86
	v_cmp_ne_u32_e32 vcc, 16, v86
	v_lshlrev_b32_e32 v86, 4, v86
	s_add_i32 m0, s48, 0xec00
	v_cndmask_b32_e32 v86, 0, v86, vcc
	v_lshl_add_u32 v84, v85, 9, v86
	global_load_lds_dwordx4 v84, s[70:71]
	s_cmp_gt_u32 s50, 2
	s_cbranch_scc1 .Lde_s6
	v_add_u32_e32 v84, 2048, v193
	v_mul_u32_u24_e32 v85, 0xf10, v84
	v_lshrrev_b32_e32 v85, 16, v85
	v_mul_u32_u24_e32 v86, 17, v85
	v_sub_u32_e32 v86, v84, v86
	v_cmp_ne_u32_e32 vcc, 16, v86
	v_lshlrev_b32_e32 v86, 4, v86
	s_add_i32 m0, s48, 0x10c00
	v_cndmask_b32_e32 v86, 0, v86, vcc
	v_lshl_add_u32 v84, v85, 9, v86
	global_load_lds_dwordx4 v84, s[70:71]
.Lde_s6:
.LBB9_399:
	s_mov_b32 s43, 0
	v_mov_b32_e32 v0, v196

; #define LAS __attribute__((address_space(3)))
; __device__ __forceinline__ bool attn_unit(const Ptrs& P, LAS unsigned char* lds, int unit, int tid, int wave, int lane, bool pre, int nxt) {
;     ...
;         if (c == 4 && pf) { const int kh2 = (nxt >> 5) & 3, b2 = nxt >> 7; const bf16_t* kb_ = (const bf16_t*)(ws + WS_K) + (size_t)b2 * SEQ * KVW + kh2 * 64 + (size_t)(n2 - 1) * 128 * KVW; const bf16_t* vb_ = (const bf16_t*)(ws + WS_VT) + (size_t)(b2 * 4 + kh2) * 64 * SEQ + (n2 - 1) * 128;
;             for (int i_ = wave; i_ < 35; i_ += 8) {
;                 if (i_ < 18) { const int q_ = 64 * i_ + lane, row_ = q_ / 9; int seg_ = q_ - 9 * row_; seg_ = seg_ == 8 ? 0 : seg_;
;                     __builtin_amdgcn_global_load_lds((const unsigned*)(kb_ + (size_t)row_ * KVW + seg_ * 8), (LAS unsigned*)(lds + i_ * 1024), 16, 0, 0); }
;                 else { const int q_ = 64 * (i_ - 18) + lane, row_ = q_ / 17; int seg_ = q_ - 17 * row_; seg_ = seg_ == 16 ? 0 : seg_;
;                     __builtin_amdgcn_global_load_lds((const unsigned*)(vb_ + (size_t)row_ * SEQ + seg_ * 8), (LAS unsigned*)(lds + AT_KB + (i_ - 18) * 1024), 16, 0, 0); } } }
.LBB9_405:
	s_lshl_b32 s48, s50, 10
	v_mov_b32_e32 v84, v192
	v_mul_u32_u24_e32 v85, 0x1c72, v84
	v_lshrrev_b32_e32 v85, 16, v85
	v_mul_u32_u24_e32 v86, 9, v85
	v_sub_u32_e32 v86, v84, v86
	v_cmp_ne_u32_e32 vcc, 8, v86
	v_lshlrev_b32_e32 v86, 4, v86
	s_add_i32 m0, s48, 0x0
	v_cndmask_b32_e32 v86, 0, v86, vcc
	v_lshl_add_u32 v84, v85, 9, v86
	global_load_lds_dwordx4 v84, s[82:83]
	v_add_u32_e32 v84, 512, v192
	v_mul_u32_u24_e32 v85, 0x1c72, v84
	v_lshrrev_b32_e32 v85, 16, v85
	v_mul_u32_u24_e32 v86, 9, v85
	v_sub_u32_e32 v86, v84, v86
	v_cmp_ne_u32_e32 vcc, 8, v86
	v_lshlrev_b32_e32 v86, 4, v86
	s_add_i32 m0, s48, 0x2000
	v_cndmask_b32_e32 v86, 0, v86, vcc
	v_lshl_add_u32 v84, v85, 9, v86
	global_load_lds_dwordx4 v84, s[82:83]
	s_cmp_lt_u32 s50, 2
	s_cbranch_scc1 .Ldk_s7
	v_add_u32_e32 v84, 1024, v193
	v_mul_u32_u24_e32 v85, 0xf10, v84
	v_lshrrev_b32_e32 v85, 16, v85
	v_mul_u32_u24_e32 v86, 17, v85
	v_sub_u32_e32 v86, v84, v86
	v_cmp_ne_u32_e32 vcc, 16, v86
	v_lshlrev_b32_e32 v86, 4, v86
	s_add_i32 m0, s48, 0x4000
	v_cndmask_b32_e32 v86, 0, v86, vcc
	v_lshl_add_u32 v84, v85, 13, v86
	global_load_lds_dwordx4 v84, s[74:75]
	s_branch .Ldj_s7
.Ldk_s7:
	v_add_u32_e32 v84, 1024, v192
	v_mul_u32_u24_e32 v85, 0x1c72, v84
	v_lshrrev_b32_e32 v85, 16, v85
	v_mul_u32_u24_e32 v86, 9, v85
	v_sub_u32_e32 v86, v84, v86
	v_cmp_ne_u32_e32 vcc, 8, v86
	v_lshlrev_b32_e32 v86, 4, v86
	s_add_i32 m0, s48, 0x4000
	v_cndmask_b32_e32 v86, 0, v86, vcc
	v_lshl_add_u32 v84, v85, 9, v86
	global_load_lds_dwordx4 v84, s[82:83]
.Ldj_s7:
	v_add_u32_e32 v84, 1536, v193
	v_mul_u32_u24_e32 v85, 0xf10, v84
	v_lshrrev_b32_e32 v85, 16, v85
	v_mul_u32_u24_e32 v86, 17, v85
	v_sub_u32_e32 v86, v84, v86
	v_cmp_ne_u32_e32 vcc, 16, v86
	v_lshlrev_b32_e32 v86, 4, v86
	s_add_i32 m0, s48, 0x6000
	v_cndmask_b32_e32 v86, 0, v86, vcc
	v_lshl_add_u32 v84, v85, 13, v86
	global_load_lds_dwordx4 v84, s[74:75]
	s_cmp_gt_u32 s50, 2
	s_cbranch_scc1 .Lde_s7
	v_add_u32_e32 v84, 2048, v193
	v_mul_u32_u24_e32 v85, 0xf10, v84
	v_lshrrev_b32_e32 v85, 16, v85
	v_mul_u32_u24_e32 v86, 17, v85
	v_sub_u32_e32 v86, v84, v86
	v_cmp_ne_u32_e32 vcc, 16, v86
	v_lshlrev_b32_e32 v86, 4, v86
	s_add_i32 m0, s48, 0x8000
	v_cndmask_b32_e32 v86, 0, v86, vcc
	v_lshl_add_u32 v84, v85, 13, v86
	global_load_lds_dwordx4 v84, s[74:75]
